# phase 3: the odd non-state-pass workgroups quantise their v-table rows before the attention queue (hidden under the others' attention) instead of in the HBM-bound burst behind it
# baseline (speedup 1.0000x reference)
; __device__ __forceinline__ void quantise_tables(const Args& A, int gw, int NGW, int row_lo, int row_hi) {
;     int tid_o = threadIdx.x; asm volatile("" : "+v"(tid_o)); const int lane = tid_o & 63;
;     unsigned char* T8 = A.ws + WS_T8; float* SC = (float*)(A.ws + WS_SC);
; #pragma unroll 1
;     for (int row = row_lo + gw; row < row_hi; row += 4 * NGW) {
;         f32x4 v[4][4]; int rr[4];
; #pragma unroll
;         for (int q = 0; q < 4; ++q) { const int r = row + q * NGW; rr[q] = r; const int rc = r < row_hi ? r : row;
;             const float* s = (rc < 16384 ? A.pu + (size_t)rc * 1024 : A.pv + (size_t)(rc - 16384) * 1024) + 16 * lane;
; #pragma unroll
;             for (int j = 0; j < 4; ++j) v[q][j] = *(const f32x4*)(s + 4 * j); }
.LBB0_311:
	s_cmp_lt_u32 s2, 32
	s_cbranch_scc1 .Lqv_skip
	s_bitcmp1_b32 s2, 0
	s_cbranch_scc0 .Lqv_skip
	v_writelane_b32 v237, s6, 0
	v_writelane_b32 v237, s7, 1
	v_writelane_b32 v237, s14, 2
	v_writelane_b32 v237, s15, 3
	v_writelane_b32 v237, s17, 4
	v_writelane_b32 v237, s23, 5
	v_writelane_b32 v237, s25, 6
	v_mov_b32_e32 v238, v1
	v_mov_b32_e32 v239, v3
	v_readlane_b32 s0, v236, 0
	s_nop 1
	v_add_u32_e32 v48, s0, v137
	s_add_u32 s20, s50, 0x2fe0004
	s_movk_i32 s16, 0x4000
	v_mov_b32_e32 v0, v214
	s_addc_u32 s21, s51, 0
	v_cmp_gt_i32_e32 vcc, s16, v48
	s_and_saveexec_b64 s[10:11], vcc
	s_cbranch_execz .Lqv_end
	v_and_b32_e32 v2, 63, v0
	v_lshlrev_b32_e32 v50, 4, v2
	v_mov_b32_e32 v51, 0
	v_lshl_add_u64 v[0:1], s[50:51], 0, v[50:51]
	s_mov_b64 s[0:1], 0x1000000
	v_add_u32_e32 v54, 0x4000, v48
	v_lshl_add_u64 v[52:53], v[0:1], 0, s[0:1]
	v_cmp_eq_u32_e64 s[0:1], 0, v2
	s_lshl_b32 s17, s84, 4
	s_mul_i32 s22, s84, 24
	s_mov_b64 s[12:13], 0
	v_mov_b32_e32 v49, s45
	v_mov_b32_e32 v58, s43
	v_mov_b32_e32 v59, s44
	v_mov_b32_e32 v60, s42
	v_lshlrev_b32_e32 v50, 2, v50
	s_mov_b32 s23, 0x8000
	s_mov_b32 s24, 0xda24260
	s_movk_i32 s25, 0x7fff
	s_branch .Lqv_347

; __device__ __forceinline__ void quantise_tables(const Args& A, int gw, int NGW, int row_lo, int row_hi) {
;     ...
;             if (rr[q] < row_hi) { *(u32x4*)(T8 + (size_t)rr[q] * 1024 + 16 * lane) = o4; if (lane == 0) SC[rr[q]] = sc; }
;         }
;     }
; }
.Lqv_end:
	s_or_b64 exec, exec, s[10:11]
	s_waitcnt vmcnt(0)
	v_readlane_b32 s6, v237, 0
	v_readlane_b32 s7, v237, 1
	v_readlane_b32 s14, v237, 2
	v_readlane_b32 s15, v237, 3
	v_readlane_b32 s17, v237, 4
	v_readlane_b32 s23, v237, 5
	v_readlane_b32 s25, v237, 6
	v_mov_b32_e32 v1, v238
	v_mov_b32_e32 v3, v239

; __device__ __forceinline__ void quantise_tables(const Args& A, int gw, int NGW, int row_lo, int row_hi) {
;     int tid_o = threadIdx.x; asm volatile("" : "+v"(tid_o)); const int lane = tid_o & 63;
;     unsigned char* T8 = A.ws + WS_T8; float* SC = (float*)(A.ws + WS_SC);
; #pragma unroll 1
;     for (int row = row_lo + gw; row < row_hi; row += 4 * NGW) {
;         f32x4 v[4][4]; int rr[4];
; #pragma unroll
;         for (int q = 0; q < 4; ++q) { const int r = row + q * NGW; rr[q] = r; const int rc = r < row_hi ? r : row;
;             const float* s = (rc < 16384 ? A.pu + (size_t)rc * 1024 : A.pv + (size_t)(rc - 16384) * 1024) + 16 * lane;
; #pragma unroll
;             for (int j = 0; j < 4; ++j) v[q][j] = *(const f32x4*)(s + 4 * j); }
;     ...
;         quantise_tables(A, blockIdx.x * 8 + wave, gridDim.x * 8, 16384, 32768);
.LBB0_344:
	s_or_b64 exec, exec, s[0:1]
	s_cmp_lt_u32 s2, 32
	s_cbranch_scc1 .Lqv_tail_do
	s_bitcmp1_b32 s2, 0
	s_cbranch_scc1 .Lqv_tail_skip
.Lqv_tail_do:
	s_add_u32 s20, s50, 0x2fe0004
	s_movk_i32 s16, 0x4000
	v_mov_b32_e32 v0, v214
	s_addc_u32 s21, s51, 0
	v_cmp_gt_i32_e32 vcc, s16, v48
	s_and_saveexec_b64 s[10:11], vcc
	s_cbranch_execz .LBB0_358
	v_and_b32_e32 v2, 63, v0
	v_lshlrev_b32_e32 v50, 4, v2
	v_mov_b32_e32 v51, 0
	v_lshl_add_u64 v[0:1], s[50:51], 0, v[50:51]
	s_mov_b64 s[0:1], 0x1000000
	v_add_u32_e32 v54, 0x4000, v48
	v_lshl_add_u64 v[52:53], v[0:1], 0, s[0:1]
	v_cmp_eq_u32_e64 s[0:1], 0, v2
	s_lshl_b32 s17, s84, 4
	s_mul_i32 s22, s84, 24
	s_mov_b64 s[12:13], 0
	v_mov_b32_e32 v49, s45
	v_mov_b32_e32 v58, s43
	v_mov_b32_e32 v59, s44
	v_mov_b32_e32 v60, s42
	v_lshlrev_b32_e32 v50, 2, v50
	s_mov_b32 s23, 0x8000
	s_mov_b32 s24, 0xda24260
	s_movk_i32 s25, 0x7fff
	s_branch .LBB0_347

; __device__ __forceinline__ void xcd_barrier(const XcdBarrier& b) {
;     asm volatile("s_waitcnt vmcnt(0)" ::: "memory");
;     __syncthreads();
;     if (threadIdx.x == 0) {
;         unsigned* bar = b.bar;
;         __builtin_amdgcn_s_waitcnt(0);
;         unsigned nloc = b.st[0], nx = b.st[1];
;         if (nloc == 0u) { xcd_barrier_complete(bar, b.x, nloc, nx); b.st[0] = nloc; b.st[1] = nx; }
.Lqv_tail_skip:
	s_waitcnt vmcnt(0)
	s_barrier
	s_and_saveexec_b64 s[0:1], s[18:19]
	s_cbranch_execz .LBB0_410
	s_add_i32 s4, 0, 0x23fe0
	v_mov_b32_e32 v0, s4
	s_waitcnt vmcnt(0) expcnt(0) lgkmcnt(0)
	ds_read_b32 v2, v0
	s_add_i32 s4, 0, 0x23fe4
	v_mov_b32_e32 v0, s4
	ds_read_b32 v0, v0
	s_waitcnt lgkmcnt(1)
	v_cmp_ne_u32_e32 vcc, 0, v2
	s_cbranch_vccnz .LBB0_374
	s_add_u32 s4, s50, 0xfc0200
	s_addc_u32 s5, s51, 0
	s_add_u32 s6, s50, 0xfc0400
	s_addc_u32 s7, s51, 0
	s_add_u32 s8, s50, 0xfc0500
	s_addc_u32 s9, s51, 0
	s_add_u32 s10, s50, 0xfc0600
	s_addc_u32 s11, s51, 0
	s_add_u32 s12, s50, 0xfc0700
	s_addc_u32 s13, s51, 0
	s_add_u32 s14, s50, 0xfc0800
	s_addc_u32 s15, s51, 0
	s_add_u32 s16, s50, 0xfc0900
	s_addc_u32 s17, s51, 0
	s_add_u32 s22, s50, 0xfc0a00
	s_addc_u32 s23, s51, 0
	s_add_u32 s24, s50, 0xfc0b00
	s_addc_u32 s25, s51, 0
	s_add_u32 s26, s50, 0xfc0c00
	s_addc_u32 s27, s51, 0
	s_add_u32 s28, s50, 0xfc0d00
	s_addc_u32 s29, s51, 0
	s_add_u32 s30, s50, 0xfc0e00
	s_addc_u32 s31, s51, 0
	s_add_u32 s34, s50, 0xfc0f00
	s_addc_u32 s35, s51, 0
	s_add_u32 s38, s50, 0xfc1000
	s_addc_u32 s39, s51, 0
	s_add_u32 s40, s50, 0xfc1100
	s_addc_u32 s41, s51, 0
	s_add_u32 s42, s50, 0xfc1200
	s_addc_u32 s43, s51, 0
	s_mul_i32 s33, s85, s97
	s_add_u32 s44, s50, 0xfc1300
	s_mul_i32 s33, s33, s84
	s_addc_u32 s45, s51, 0
	s_mov_b32 s72, 1
	v_mov_b32_e32 v16, 0
	s_branch .LBB0_362
